# P2: one shared counter for the three unit lists (an exhausted-list pop carries the first unit of the next list: one unsuccessful pop per workgroup instead of three) on top of the unrolled prompt index
# speedup vs baseline: 1.0065x; 1.0052x over previous
.LBB0_636:
	s_cmp_gt_i32 s28, 2
	s_cselect_b64 s[0:1], -1, 0
	s_cmp_lt_i32 s29, 3
	s_cselect_b64 s[2:3], -1, 0
	s_or_b64 s[0:1], s[0:1], s[2:3]
	s_and_b64 vcc, exec, s[0:1]
	s_cbranch_vccnz .LBB0_1534
	v_mov_b32_e32 v249, -1
	v_readlane_b32 s0, v251, 0
	s_bitcmp1_b32 s0, 2
	s_mov_b32 s27, 0
	s_cbranch_scc1 .LBB0_697
	s_waitcnt lgkmcnt(0)
	v_readlane_b32 s48, v251, 44
	v_readlane_b32 s55, v251, 51
	s_lshl_b32 s2, s55, 6
	s_ashr_i32 s3, s2, 31
	v_readlane_b32 s50, v251, 46
	s_lshl_b64 s[2:3], s[2:3], 2
	v_readlane_b32 s51, v251, 47
	s_add_u32 s2, s50, s2
	s_addc_u32 s3, s51, s3
	s_add_u32 s2, s2, 0x10000
	s_addc_u32 s3, s3, 0
	v_writelane_b32 v252, s2, 6
	v_lshrrev_b32_e32 v2, 2, v198
	v_readlane_b32 s24, v251, 1
	v_writelane_b32 v252, s3, 7
	s_lshl_b32 s2, s88, 13
	s_add_i32 s22, s2, 0
	s_add_u32 s30, s50, 0xbe00000
	s_addc_u32 s31, s51, 0
	s_lshl_b32 s2, s88, 10
	s_add_i32 s2, s2, 0
	s_lshl_b32 s23, s88, 8
	s_add_i32 s2, s2, 0x10000
	v_and_b32_e32 v3, 8, v2
	s_cmp_lt_u32 s24, 64
	v_lshlrev_b32_e32 v172, 2, v3
	v_mov_b32_e32 v173, 0
	v_readlane_b32 s4, v251, 28
	s_cselect_b64 s[34:35], -1, 0
	s_cmp_gt_u32 s24, 63
	v_lshl_add_u64 v[176:177], s[36:37], 0, v[172:173]
	s_cselect_b64 s[36:37], -1, 0
	v_lshlrev_b32_e32 v7, 4, v198
	s_add_i32 s4, 0, 0x12000
	v_add_u32_e32 v207, s4, v7
	s_add_i32 s4, 0, 0x12400
	v_add_u32_e32 v208, s4, v7
	s_add_i32 s4, 0, 0x12800
	v_add_u32_e32 v209, s4, v7
	s_add_i32 s4, 0, 0x12c00
	v_add_u32_e32 v210, s4, v7
	s_add_i32 s4, 0, 0x13000
	v_add_u32_e32 v211, s4, v7
	s_add_i32 s4, 0, 0x13400
	v_and_b32_e32 v170, 31, v0
	v_add_u32_e32 v212, s4, v7
	s_add_i32 s4, 0, 0x13800
	v_or_b32_e32 v8, 2, v3
	v_lshrrev_b32_e32 v5, 1, v0
	v_add_u32_e32 v213, s4, v7
	s_add_i32 s4, 0, 0x13c00
	v_or_b32_e32 v9, 1, v3
	v_cmp_eq_u32_e64 s[90:91], v8, v170
	v_or_b32_e32 v8, 4, v3
	v_lshrrev_b32_e32 v1, 5, v198
	v_readlane_b32 s18, v251, 42
	v_readlane_b32 s19, v251, 43
	v_and_b32_e32 v4, 3, v0
	v_and_b32_e32 v6, 12, v5
	v_add_u32_e32 v214, s4, v7
	v_cmp_eq_u32_e64 s[66:67], v3, v170
	v_cmp_eq_u32_e64 s[92:93], v9, v170
	v_or_b32_e32 v9, 3, v3
	v_cmp_eq_u32_e64 s[94:95], v8, v170
	v_or_b32_e32 v8, 6, v3
	v_or_b32_e32 v3, 5, v3
	v_readlane_b32 s4, v251, 0
	v_lshl_add_u64 v[174:175], s[18:19], 0, v[172:173]
	v_or3_b32 v179, s23, v6, v4
	v_lshl_add_u64 v[184:185], s[38:39], 0, v[172:173]
	v_lshl_add_u64 v[186:187], s[40:41], 0, v[172:173]
	v_cmp_eq_u32_e64 s[56:57], v3, v170
	v_or_b32_e32 v3, 7, v2
	s_bitcmp0_b32 s4, 7
	v_and_or_b32 v2, v2, 4, v4
	v_lshlrev_b32_e32 v4, 9, v1
	s_movk_i32 s20, 0xc0
	v_lshlrev_b32_e32 v172, 1, v170
	s_cselect_b64 s[38:39], -1, 0
	v_and_or_b32 v4, v7, s20, v4
	v_lshl_add_u64 v[188:189], s[50:51], 0, v[172:173]
	s_mov_b64 s[20:21], 0x11300000
	s_cmp_eq_u32 s88, 7
	v_lshl_add_u64 v[190:191], v[188:189], 0, s[20:21]
	s_cselect_b64 s[20:21], -1, 0
	s_and_b64 s[40:41], s[38:39], s[20:21]
	s_bitcmp0_b32 s4, 8
	s_cselect_b64 s[44:45], -1, 0
	s_add_i32 s20, s88, -1
	s_bfe_u32 s4, s24, 0x30006
	v_lshlrev_b32_e32 v6, 2, v198
	s_cmp_gt_u32 s20, 6
	v_add_u32_e32 v199, s2, v6
	v_cmp_gt_u32_e64 s[2:3], 16, v170
	v_cmp_eq_u32_e64 s[28:29], v8, v170
	v_lshlrev_b32_e32 v8, 6, v0
	s_cselect_b64 s[46:47], -1, 0
	s_and_b32 s58, s88, 0x3fffff8
	v_readlane_b32 s49, v251, 45
	v_lshlrev_b32_e32 v178, 3, v1
	v_cndmask_b32_e64 v180, 0, 1.0, s[2:3]
	v_and_b32_e32 v8, 0x7c0, v8
	v_lshlrev_b32_e32 v2, 3, v2
	v_lshlrev_b32_e32 v172, 2, v170
	s_cmp_lg_u32 s4, 0
	v_xor_b32_e32 v182, 0x80000000, v180
	v_cmp_eq_u32_e64 s[64:65], v3, v170
	v_add_u32_e32 v3, s22, v178
	v_add3_u32 v215, v2, s22, v4
	v_lshl_add_u64 v[192:193], s[48:49], 0, v[172:173]
	v_add_u32_e32 v2, s22, v8
	s_cselect_b64 s[48:49], -1, 0
	s_add_i32 s20, 0, 0x10200
	v_and_b32_e32 v172, 16, v5
	v_add_u32_e32 v4, 0, v6
	v_cmp_eq_u32_e64 s[0:1], 0, v0
	v_bfe_u32 v171, v198, 2, 1
	v_and_b32_e32 v206, 15, v0
	s_brev_b32 s33, 1
	v_cmp_eq_u32_e64 s[96:97], v9, v170
	v_add_u32_e32 v216, 0x1000, v215
	v_lshlrev_b32_e32 v217, 6, v1
	v_lshlrev_b32_e32 v218, 2, v1
	v_mov_b32_e32 v181, v180
	v_mov_b32_e32 v183, v182
	v_writelane_b32 v252, s4, 4
	v_add_u32_e32 v219, s20, v6
	v_lshl_add_u64 v[194:195], s[50:51], 0, v[172:173]
	v_add_u32_e32 v220, 0x10000, v4
	v_add_u32_e32 v221, 0x10200, v4
	v_lshl_add_u32 v222, v1, 11, s23
	s_add_i32 s59, 0, 0x25040
	s_mov_b32 s60, 0x3fb8aa3b
	s_mov_b32 s61, 0xc2ce8ed0
	s_mov_b32 s62, 0x42b17218
	s_brev_b32 s82, 18
	s_mov_b32 s83, 0xfe5163ab
	s_mov_b32 s84, 0x3c439041
	s_mov_b32 s63, 0xdb629599
	s_mov_b32 s85, 0xf534ddc0
	s_mov_b32 s68, 0xfc2757d1
	s_mov_b32 s69, 0x4e441529
	s_mov_b32 s70, 0xa2f9836e
	s_mov_b32 s71, 0x3fc90fda
	s_mov_b32 s72, 0x3f22f983
	s_mov_b32 s73, 0xbfc90fda
	v_mov_b32_e32 v223, 0x3c0881c4
	v_mov_b32_e32 v224, 0xbab64f3b
	s_movk_i32 s74, 0x1f8
	s_movk_i32 s75, 0x7fff
	s_mov_b32 s76, 0x7060302
	s_mov_b32 s77, 0x5040100
	v_add_u32_e32 v225, v3, v8
	s_mov_b32 s78, 0x5798000
	s_mov_b32 s79, 0x5998000
	v_mov_b32_e32 v226, 0x7f800000
	v_not_b32_e32 v227, 63
	v_not_b32_e32 v228, 31
	v_mov_b32_e32 v229, 0x7fc00000
	v_add_u32_e32 v230, v2, v178
	v_readlane_b32 s52, v251, 48
	v_readlane_b32 s53, v251, 49
	v_readlane_b32 s54, v251, 50
	v_readlane_b32 s5, v251, 29
	v_readlane_b32 s6, v251, 30
	v_readlane_b32 s7, v251, 31
	v_readlane_b32 s8, v251, 32
	v_readlane_b32 s9, v251, 33
	v_readlane_b32 s10, v251, 34
	v_readlane_b32 s11, v251, 35
	v_readlane_b32 s12, v251, 36
	v_readlane_b32 s13, v251, 37
	v_readlane_b32 s14, v251, 38
	v_readlane_b32 s15, v251, 39
	v_readlane_b32 s16, v251, 40
	v_readlane_b32 s17, v251, 41
	s_branch .LBB0_642

.LBB0_646:
	s_or_b64 exec, exec, s[20:21]
	v_mov_b32_e32 v2, s59
	s_waitcnt lgkmcnt(0)
	s_barrier
	ds_read_b32 v2, v2
	s_movk_i32 s20, 0x7f
	s_waitcnt lgkmcnt(0)
	v_mov_b32_e32 v249, v2
	v_cmp_lt_i32_e32 vcc, s20, v2
	v_readfirstlane_b32 s26, v2
	s_mov_b64 s[20:21], -1
	s_cbranch_vccnz .LBB0_641
	s_ashr_i32 s50, s26, 1
	s_ashr_i32 s51, s50, 31
	v_readlane_b32 s4, v251, 28
	s_lshl_b64 s[20:21], s[50:51], 2
	v_readlane_b32 s16, v251, 40
	v_readlane_b32 s17, v251, 41
	s_add_u32 s20, s16, s20
	s_addc_u32 s21, s17, s21
	global_load_dword v4, v173, s[20:21]
	v_lshl_or_b32 v14, s50, 6, v170
	v_ashrrev_i32_e32 v15, 31, v14
	v_readlane_b32 s14, v251, 38
	v_readlane_b32 s15, v251, 39
	v_lshlrev_b64 v[2:3], 2, v[14:15]
	v_readlane_b32 s12, v251, 36
	v_lshl_add_u64 v[6:7], s[14:15], 0, v[2:3]
	v_readlane_b32 s13, v251, 37
	global_load_dword v23, v[6:7], off
	v_readlane_b32 s5, v251, 29
	v_lshl_add_u64 v[8:9], s[12:13], 0, v[2:3]
	global_load_dword v22, v[8:9], off
	v_readlane_b32 s6, v251, 30
	v_readlane_b32 s7, v251, 31
	v_readlane_b32 s8, v251, 32
	v_readlane_b32 s9, v251, 33
	v_readlane_b32 s10, v251, 34
	v_readlane_b32 s11, v251, 35
	v_readlane_b32 s18, v251, 42
	v_readlane_b32 s19, v251, 43
	s_waitcnt vmcnt(2)
	v_mul_f32_e32 v2, 0x3fb8aa3b, v4
	v_fma_f32 v3, v4, s60, -v2
	v_rndne_f32_e32 v5, v2
	v_fmac_f32_e32 v3, 0x32a5705f, v4
	v_sub_f32_e32 v2, v2, v5
	v_add_f32_e32 v2, v2, v3
	v_cvt_i32_f32_e32 v5, v5
	v_exp_f32_e32 v2, v2
	v_cmp_ngt_f32_e32 vcc, s61, v4
	v_ldexp_f32 v2, v2, v5
	s_nop 0
	v_cndmask_b32_e32 v2, 0, v2, vcc
	v_cmp_nlt_f32_e32 vcc, s62, v4
	s_nop 1
	v_cndmask_b32_e32 v16, v226, v2, vcc
	s_waitcnt vmcnt(1)
	v_mul_f32_e32 v26, v16, v23
	v_and_b32_e32 v27, 0x7fffffff, v26
	v_cmp_nlt_f32_e64 s[52:53], |v26|, s82
	s_and_saveexec_b64 s[20:21], s[52:53]
	s_xor_b64 s[54:55], exec, s[20:21]
	s_cbranch_execz .LBB0_649
	v_lshrrev_b32_e32 v2, 23, v27
	v_add_u32_e32 v2, 0xffffff88, v2
	v_cmp_lt_u32_e32 vcc, 63, v2
	s_nop 1
	v_cndmask_b32_e32 v3, 0, v227, vcc
	v_add_u32_e32 v2, v3, v2
	v_cmp_lt_u32_e64 s[20:21], 31, v2
	s_nop 1
	v_cndmask_b32_e64 v3, 0, v228, s[20:21]
	v_add_u32_e32 v2, v3, v2
	v_cmp_lt_u32_e64 s[22:23], 31, v2
	s_nop 1
	v_cndmask_b32_e64 v3, 0, v228, s[22:23]
	v_add_u32_e32 v17, v3, v2
	v_and_b32_e32 v2, 0x7fffff, v27
	v_or_b32_e32 v24, 0x800000, v2
	v_mad_u64_u32 v[2:3], s[24:25], v24, s83, 0
	v_mov_b32_e32 v172, v3
	v_mad_u64_u32 v[4:5], s[24:25], v24, s84, v[172:173]
	v_mov_b32_e32 v172, v5
	v_mad_u64_u32 v[10:11], s[24:25], v24, s63, v[172:173]
	v_mov_b32_e32 v172, v11
	v_mad_u64_u32 v[12:13], s[24:25], v24, s85, v[172:173]
	v_mov_b32_e32 v172, v13
	v_mad_u64_u32 v[18:19], s[24:25], v24, s68, v[172:173]
	v_mov_b32_e32 v172, v19
	v_mad_u64_u32 v[20:21], s[24:25], v24, s69, v[172:173]
	v_mov_b32_e32 v172, v21
	v_mad_u64_u32 v[24:25], s[24:25], v24, s70, v[172:173]
	v_cndmask_b32_e32 v3, v20, v12, vcc
	v_cndmask_b32_e32 v5, v24, v18, vcc
	v_cndmask_b32_e32 v13, v25, v20, vcc
	v_cndmask_b32_e64 v11, v5, v3, s[20:21]
	v_cndmask_b32_e64 v5, v13, v5, s[20:21]
	v_cndmask_b32_e32 v13, v18, v10, vcc
	v_cndmask_b32_e64 v3, v3, v13, s[20:21]
	v_cndmask_b32_e32 v4, v12, v4, vcc
	v_cndmask_b32_e64 v5, v5, v11, s[22:23]
	v_cndmask_b32_e64 v11, v11, v3, s[22:23]
	v_sub_u32_e32 v18, 32, v17
	v_cndmask_b32_e64 v12, v13, v4, s[20:21]
	v_alignbit_b32 v19, v5, v11, v18
	v_cmp_eq_u32_e64 s[24:25], 0, v17
	v_cndmask_b32_e64 v3, v3, v12, s[22:23]
	v_alignbit_b32 v13, v11, v3, v18
	v_cndmask_b32_e64 v5, v19, v5, s[24:25]
	v_cndmask_b32_e32 v2, v10, v2, vcc
	v_cndmask_b32_e64 v11, v13, v11, s[24:25]
	v_bfe_u32 v19, v5, 29, 1
	v_cndmask_b32_e64 v2, v4, v2, s[20:21]
	v_alignbit_b32 v13, v5, v11, 30
	v_sub_u32_e32 v20, 0, v19
	v_cndmask_b32_e64 v2, v12, v2, s[22:23]
	v_xor_b32_e32 v13, v13, v20
	v_alignbit_b32 v4, v3, v2, v18
	v_cndmask_b32_e64 v3, v4, v3, s[24:25]
	v_ffbh_u32_e32 v10, v13
	v_alignbit_b32 v4, v11, v3, 30
	v_min_u32_e32 v10, 32, v10
	v_alignbit_b32 v2, v3, v2, 30
	v_xor_b32_e32 v4, v4, v20
	v_sub_u32_e32 v11, 31, v10
	v_xor_b32_e32 v2, v2, v20
	v_alignbit_b32 v12, v13, v4, v11
	v_alignbit_b32 v2, v4, v2, v11
	v_alignbit_b32 v3, v12, v2, 9
	v_ffbh_u32_e32 v4, v3
	v_min_u32_e32 v4, 32, v4
	v_lshrrev_b32_e32 v17, 29, v5
	v_not_b32_e32 v11, v4
	v_alignbit_b32 v2, v3, v2, v11
	v_lshlrev_b32_e32 v3, 31, v17
	v_or_b32_e32 v11, 0x33000000, v3
	v_add_lshl_u32 v4, v4, v10, 23
	v_lshrrev_b32_e32 v2, 9, v2
	v_sub_u32_e32 v4, v11, v4
	v_or_b32_e32 v3, 0.5, v3
	v_lshlrev_b32_e32 v10, 23, v10
	v_or_b32_e32 v2, v4, v2
	v_lshrrev_b32_e32 v4, 9, v12
	v_sub_u32_e32 v3, v3, v10
	v_or_b32_e32 v3, v4, v3
	v_mul_f32_e32 v4, 0x3fc90fda, v3
	v_fma_f32 v10, v3, s71, -v4
	v_fmac_f32_e32 v10, 0x33a22168, v3
	v_fmac_f32_e32 v10, 0x3fc90fda, v2
	v_lshrrev_b32_e32 v2, 30, v5
	v_add_f32_e32 v30, v4, v10
	v_add_u32_e32 v29, v19, v2
	s_andn2_saveexec_b64 s[20:21], s[54:55]
	s_branch .LBB0_650

.LBB0_697:
	v_readlane_b32 s4, v251, 0
	v_readlane_b32 s24, v251, 44
	v_writelane_b32 v252, s89, 12
	s_bitcmp1_b32 s4, 3
	s_mul_i32 s2, s88, 0x1c00
	v_mul_u32_u24_e32 v151, 12, v198
	v_readlane_b32 s25, v251, 45
	v_readlane_b32 s26, v251, 46
	v_readlane_b32 s27, v251, 47
	v_readlane_b32 s28, v251, 48
	v_readlane_b32 s29, v251, 49
	v_readlane_b32 s31, v251, 51
	v_readlane_b32 s30, v251, 50
	s_cbranch_scc1 .LBB0_1067
	v_cmp_eq_u32_e64 s[0:1], 0, v0
	v_lshlrev_b32_e32 v1, 6, v0
	v_and_b32_e32 v74, 0x3c0, v1
	v_writelane_b32 v252, s0, 13
	v_mov_b32_e32 v75, 0
	v_lshl_add_u64 v[2:3], s[26:27], 0, v[74:75]
	v_writelane_b32 v252, s1, 14
	s_lshl_b32 s0, s31, 6
	s_add_i32 s0, s0, 0
	s_ashr_i32 s1, s0, 31
	s_lshl_b64 s[0:1], s[0:1], 2
	s_add_u32 s0, s26, s0
	s_addc_u32 s1, s27, s1
	s_add_u32 s0, s0, 0x10000
	s_addc_u32 s1, s1, 0
	v_writelane_b32 v252, s0, 15
	v_lshrrev_b32_e32 v152, 4, v0
	v_and_b32_e32 v150, 31, v0
	v_writelane_b32 v252, s1, 16
	s_lshl_b32 s0, s88, 8
	s_add_i32 s6, s0, 0
	s_mov_b64 s[0:1], 0xb100000
	v_lshl_add_u64 v[76:77], v[2:3], 0, s[0:1]
	s_movk_i32 s0, 0x410
	v_mad_u32_u24 v6, v152, s0, 0
	s_add_u32 s0, s26, 0xbc00000
	s_addc_u32 s1, s27, 0
	v_writelane_b32 v252, s0, 17
	v_lshrrev_b32_e32 v2, 1, v198
	v_and_b32_e32 v2, 16, v2
	v_writelane_b32 v252, s1, 18
	s_mul_i32 s0, s88, 0x300
	s_add_i32 s33, s6, s0
	s_add_u32 s0, s26, 0x14d00000
	s_addc_u32 s1, s27, 0
	s_add_i32 s54, s33, s2
	v_mov_b32_e32 v3, v75
	v_writelane_b32 v252, s2, 19
	v_lshl_add_u64 v[4:5], s[26:27], 0, v[2:3]
	s_mov_b64 s[2:3], 0xba00000
	s_bitcmp0_b32 s4, 5
	v_lshl_add_u64 v[78:79], v[4:5], 0, s[2:3]
	s_cselect_b64 s[2:3], -1, 0
	v_writelane_b32 v252, s2, 21
	v_mul_u32_u24_e32 v4, 0x410, v150
	v_add3_u32 v154, 0, v4, v2
	v_writelane_b32 v252, s3, 22
	s_add_u32 s2, s26, 0x14a00000
	v_writelane_b32 v252, s2, 23
	s_addc_u32 s2, s27, 0
	s_bitcmp0_b32 s4, 6
	v_readlane_b32 s4, v251, 1
	v_lshl_add_u64 v[80:81], s[0:1], 0, v[2:3]
	v_writelane_b32 v252, s2, 25
	s_cselect_b64 s[2:3], -1, 0
	s_cmpk_lt_u32 s4, 0x800
	v_lshlrev_b32_e32 v2, 4, v198
	s_cselect_b64 s[4:5], -1, 0
	v_lshl_add_u64 v[84:85], s[0:1], 0, v[2:3]
	s_movk_i32 s0, 0x7e0
	s_and_b64 s[2:3], s[2:3], s[4:5]
	v_bitop3_b32 v159, v1, s0, v198 bitop3:0xc8
	s_lshl_b32 s0, s88, 13
	v_writelane_b32 v252, s2, 27
	v_lshlrev_b32_e32 v2, 7, v0
	v_lshrrev_b32_e32 v3, 2, v198
	s_add_i32 s0, s0, 0
	v_writelane_b32 v252, s3, 28
	v_lshlrev_b32_e32 v82, 2, v198
	v_and_b32_e32 v2, 0x80, v2
	v_and_b32_e32 v3, 12, v3
	s_add_i32 s86, s0, 0xc800
	s_add_i32 s0, 0, 0x25040
	v_add_u32_e32 v155, s33, v82
	v_add3_u32 v157, s6, v2, v3
	v_lshlrev_b32_e32 v2, 1, v0
	v_writelane_b32 v252, s0, 29
	s_waitcnt lgkmcnt(0)
	s_mov_b32 s47, 0
	v_lshl_or_b32 v153, s88, 5, v150
	v_or_b32_e32 v86, 1, v82
	v_or_b32_e32 v88, 2, v82
	v_or_b32_e32 v90, 3, v82
	s_movk_i32 s55, 0x100
	v_or_b32_e32 v92, 0x100, v82
	v_or_b32_e32 v94, 0x101, v82
	v_or_b32_e32 v96, 0x102, v82
	v_or_b32_e32 v98, 0x103, v82
	v_or_b32_e32 v100, 0x200, v82
	v_or_b32_e32 v102, 0x201, v82
	v_or_b32_e32 v104, 0x202, v82
	v_or_b32_e32 v106, 0x203, v82
	v_or_b32_e32 v108, 0x300, v82
	v_or_b32_e32 v110, 0x301, v82
	v_or_b32_e32 v112, 0x302, v82
	v_or_b32_e32 v114, 0x303, v82
	v_or_b32_e32 v116, 0x400, v82
	v_or_b32_e32 v118, 0x401, v82
	v_or_b32_e32 v120, 0x402, v82
	v_or_b32_e32 v122, 0x403, v82
	v_or_b32_e32 v124, 0x500, v82
	v_or_b32_e32 v126, 0x501, v82
	v_or_b32_e32 v128, 0x502, v82
	v_or_b32_e32 v130, 0x503, v82
	v_or_b32_e32 v132, 0x600, v82
	v_or_b32_e32 v134, 0x601, v82
	v_or_b32_e32 v136, 0x602, v82
	v_or_b32_e32 v138, 0x603, v82
	v_or_b32_e32 v140, 0x700, v82
	v_or_b32_e32 v142, 0x701, v82
	v_or_b32_e32 v144, 0x702, v82
	v_or_b32_e32 v146, 0x703, v82
	v_add_u32_e32 v156, s6, v82
	v_and_b32_e32 v158, 28, v2
	s_movk_i32 s87, 0xff
	v_add_u32_e32 v160, v6, v74
	v_mov_b32_e32 v161, 1
	v_mov_b32_e32 v162, 0xff800000
	v_mov_b32_e32 v163, 0x7f800000
	v_add_u32_e32 v164, v155, v151
	v_writelane_b32 v252, s54, 31
	s_branch .LBB0_702
.Lq_exit_p:
	v_mov_b32_e32 v249, v1
	s_branch .LBB0_701

.LBB0_702:
	s_waitcnt vmcnt(0)
	s_barrier
	v_readfirstlane_b32 s2, v249
	s_cmp_lt_i32 s2, 0
	s_cbranch_scc1 .Lq_pop_p
	v_mov_b32_e32 v1, v249
	v_mov_b32_e32 v249, -1
	s_mov_b64 s[0:1], -1
	s_branch .Lq_have_p
.Lq_pop_p:
	s_mov_b64 s[0:1], exec
	v_readlane_b32 s2, v252, 13
	v_readlane_b32 s3, v252, 14
	s_and_b64 s[2:3], s[0:1], s[2:3]
	s_mov_b64 exec, s[2:3]
	s_cbranch_execz .LBB0_706
	s_mov_b64 s[4:5], exec
	v_mbcnt_lo_u32_b32 v1, s4, 0
	v_mbcnt_hi_u32_b32 v1, s5, v1
	v_cmp_eq_u32_e32 vcc, 0, v1
	s_and_saveexec_b64 s[2:3], vcc
	s_cbranch_execz .LBB0_705
	s_bcnt1_i32_b64 s4, s[4:5]
	v_mov_b32_e32 v2, s4
	v_readlane_b32 s4, v252, 15
	v_readlane_b32 s5, v252, 16
	s_nop 4
	global_atomic_add v2, v75, v2, s[4:5] sc0

.Lq_have_p:
	v_add_u32_e32 v1, 0xffffff80, v1
	v_cmp_lt_i32_e32 vcc, s87, v1
	v_readfirstlane_b32 s2, v1
	s_cbranch_vccnz .Lq_exit_p
	s_ashr_i32 s0, s2, 2
	s_and_b32 s4, s2, 3
	s_sub_i32 s5, 63, s0
	s_lshl_b32 s2, s4, 11
	s_lshl_b32 s89, s5, 5
	s_add_i32 s13, s89, s2
	v_or_b32_e32 v74, s13, v152
	v_lshlrev_b64 v[2:3], 10, v[74:75]
	v_or_b32_e32 v74, s13, v150
	v_readlane_b32 s0, v252, 17
	v_lshlrev_b64 v[18:19], 5, v[74:75]
	v_readlane_b32 s1, v252, 18
	v_lshl_add_u64 v[14:15], v[76:77], 0, v[2:3]
	global_load_dwordx4 v[2:5], v[14:15], off offset:48
	global_load_dwordx4 v[6:9], v[14:15], off offset:32
	global_load_dwordx4 v[10:13], v[14:15], off offset:16
	s_nop 0
	global_load_dwordx4 v[14:17], v[14:15], off
	v_lshl_add_u64 v[18:19], s[0:1], 0, v[18:19]
	global_load_dwordx4 v[184:187], v[18:19], off
	global_load_dwordx4 v[188:191], v[18:19], off offset:16
	v_add_u32_e32 v192, s2, v153
	v_mov_b32_e32 v193, 0
	v_lshlrev_b64 v[192:193], 7, v[192:193]
	v_lshl_add_u64 v[192:193], v[78:79], 0, v[192:193]
	global_load_dwordx4 v[26:29], v[192:193], off
	global_load_dwordx4 v[30:33], v[192:193], off offset:32
	global_load_dwordx4 v[34:37], v[192:193], off offset:64
	global_load_dwordx4 v[38:41], v[192:193], off offset:96
	s_cmp_le_i32 s88, s5
	s_cselect_b64 s[0:1], -1, 0
	s_waitcnt vmcnt(6)
	ds_write_b128 v160, v[14:17]
	ds_write_b128 v160, v[10:13] offset:16
	ds_write_b128 v160, v[6:9] offset:32
	ds_write_b128 v160, v[2:5] offset:48
	s_waitcnt vmcnt(4)
	v_mul_f32_e32 v18, 0x3d3504f3, v184
	v_mul_f32_e32 v20, 0x3d3504f3, v188
	v_mul_f32_e32 v1, 0x3d3504f3, v185
	v_mul_f32_e32 v19, 0x3d3504f3, v189
	v_mul_f32_e32 v22, 0x3d3504f3, v186
	v_mul_f32_e32 v24, 0x3d3504f3, v190
	v_mul_f32_e32 v21, 0x3d3504f3, v187
	v_mul_f32_e32 v23, 0x3d3504f3, v191
	s_waitcnt lgkmcnt(0)
	s_barrier

.LBB0_1067:
	s_bitcmp1_b32 s4, 4
	s_mov_b32 s89, 0
	s_cbranch_scc1 .LBB0_1484
	s_lshl_b32 s0, s31, 6
	s_addk_i32 s0, 0
	s_ashr_i32 s1, s0, 31
	s_lshl_b64 s[0:1], s[0:1], 2
	s_add_u32 s0, s26, s0
	s_addc_u32 s1, s27, s1
	s_add_u32 s0, s0, 0x10000
	s_addc_u32 s1, s1, 0
	v_and_b32_e32 v196, 7, v0
	v_writelane_b32 v253, s0, 45
	v_lshrrev_b32_e32 v1, 5, v198
	v_lshlrev_b32_e32 v98, 7, v196
	v_mov_b32_e32 v99, 0
	v_writelane_b32 v253, s1, 46
	s_lshl_b32 s0, s88, 10
	v_lshl_add_u64 v[2:3], s[26:27], 0, v[98:99]
	v_lshlrev_b32_e32 v98, 4, v1
	s_add_i32 s33, s0, 0
	v_lshl_add_u64 v[2:3], v[2:3], 0, v[98:99]
	s_mov_b64 s[0:1], 0xb100000
	v_lshl_add_u64 v[100:101], v[2:3], 0, s[0:1]
	s_add_i32 s82, s33, s2
	v_lshlrev_b32_e32 v2, 2, v196
	v_mov_b32_e32 v3, v99
	v_readlane_b32 s6, v251, 1
	v_lshl_add_u64 v[2:3], s[26:27], 0, v[2:3]
	s_mov_b64 s[0:1], 0xbc00000
	s_cmpk_lt_u32 s6, 0x1000
	v_lshl_add_u64 v[102:103], v[2:3], 0, s[0:1]
	s_cselect_b64 s[0:1], -1, 0
	v_and_b32_e32 v194, 31, v0
	v_writelane_b32 v252, s0, 4
	s_lshl_b32 s90, s88, 11
	s_lshr_b32 s8, s6, 8
	v_writelane_b32 v252, s1, 5
	v_lshlrev_b32_e32 v197, 6, v194
	s_and_b32 s0, s90, 0x1800
	v_lshlrev_b32_e32 v4, 3, v1
	v_or_b32_e32 v1, s0, v197
	s_waitcnt lgkmcnt(0)
	v_readlane_b32 s36, v251, 6
	s_cmpk_lt_u32 s6, 0x1040
	v_lshlrev_b32_e32 v2, 2, v1
	v_mov_b32_e32 v3, v99
	v_readlane_b32 s44, v251, 14
	v_readlane_b32 s45, v251, 15
	s_cselect_b64 s[0:1], -1, 0
	v_and_b32_e32 v6, 32, v198
	v_lshl_add_u64 v[2:3], s[44:45], 0, v[2:3]
	v_mov_b32_e32 v7, v99
	v_writelane_b32 v252, s0, 8
	v_lshl_add_u64 v[104:105], v[2:3], 0, v[6:7]
	v_lshl_add_u64 v[2:3], s[26:27], 0, v[98:99]
	v_writelane_b32 v252, s1, 9
	s_mov_b64 s[0:1], 0xba00000
	s_cmpk_lt_u32 s6, 0x100
	v_lshlrev_b32_e32 v108, 2, v198
	v_lshl_add_u64 v[106:107], v[2:3], 0, s[0:1]
	s_cselect_b64 s[0:1], -1, 0
	v_cmp_gt_u32_e64 s[10:11], s88, v108
	v_writelane_b32 v252, s0, 6
	s_add_i32 s6, s88, 0x801
	v_or_b32_e32 v174, 0x800, v108
	v_writelane_b32 v253, s10, 43
	v_or_b32_e32 v178, 0x802, v108
	v_or_b32_e32 v180, 0x803, v108
	v_writelane_b32 v252, s1, 7
	v_cmp_gt_u32_e64 s[30:31], s6, v174
	v_writelane_b32 v253, s11, 44
	v_cmp_le_u32_e64 s[54:55], s6, v178
	v_cmp_gt_u32_e64 s[10:11], s6, v178
	v_cmp_le_u32_e64 s[56:57], s6, v180
	v_cmp_gt_u32_e64 s[6:7], s6, v180
	v_cmp_eq_u32_e64 s[34:35], 0, v0
	s_add_u32 s64, s26, 0x14c00000
	v_lshlrev_b32_e32 v98, 4, v198
	v_writelane_b32 v252, s6, 33
	s_addc_u32 s65, s27, 0
	v_lshl_add_u64 v[2:3], s[26:27], 0, v[98:99]
	s_mov_b64 s[0:1], 0x18d00000
	v_writelane_b32 v252, s7, 34
	s_lshl_b64 s[6:7], s[88:89], 7
	v_lshlrev_b32_e32 v98, 5, v196
	v_and_b32_e32 v1, 32, v0
	v_writelane_b32 v254, s34, 25
	v_lshl_add_u64 v[110:111], v[2:3], 0, s[0:1]
	v_lshl_add_u64 v[2:3], s[6:7], 0, v[98:99]
	v_lshrrev_b32_e32 v1, 1, v1
	v_writelane_b32 v254, s35, 26
	v_readlane_b32 s37, v251, 7
	v_readlane_b32 s38, v251, 8
	v_readlane_b32 s39, v251, 9
	v_readlane_b32 s40, v251, 10
	v_readlane_b32 s41, v251, 11
	v_readlane_b32 s42, v251, 12
	v_readlane_b32 s43, v251, 13
	v_readlane_b32 s46, v251, 16
	v_readlane_b32 s47, v251, 17
	v_readlane_b32 s48, v251, 18
	v_readlane_b32 s49, v251, 19
	v_readlane_b32 s50, v251, 20
	v_readlane_b32 s51, v251, 21
	v_or_b32_e32 v2, v2, v1
	v_writelane_b32 v254, s64, 27
	v_lshl_add_u64 v[2:3], s[26:27], 0, v[2:3]
	v_readlane_b32 s36, v251, 28
	v_writelane_b32 v254, s65, 28
	v_lshl_add_u64 v[182:183], v[2:3], 0, s[0:1]
	s_add_i32 s0, s88, 8
	v_readlane_b32 s37, v251, 29
	v_writelane_b32 v254, s30, 29
	v_cmp_le_u32_e64 s[52:53], s88, v108
	s_and_b32 s0, s0, 0x7fffffc
	s_mov_b64 s[12:13], s[36:37]
	v_writelane_b32 v254, s31, 30
	s_add_u32 s0, s12, s0
	v_writelane_b32 v254, s52, 31
	s_addc_u32 s1, s13, 0
	v_writelane_b32 v252, s0, 35
	v_writelane_b32 v254, s53, 32
	v_writelane_b32 v254, s54, 33
	v_writelane_b32 v252, s1, 36
	s_lshl_b32 s0, s88, 13
	v_writelane_b32 v254, s55, 34
	v_writelane_b32 v253, s10, 41
	v_add_u32_e32 v199, s33, v108
	v_readlane_b32 s38, v251, 30
	v_readlane_b32 s39, v251, 31
	v_readlane_b32 s40, v251, 32
	v_readlane_b32 s41, v251, 33
	v_readlane_b32 s42, v251, 34
	v_readlane_b32 s43, v251, 35
	v_readlane_b32 s44, v251, 36
	v_readlane_b32 s45, v251, 37
	v_readlane_b32 s46, v251, 38
	v_readlane_b32 s47, v251, 39
	v_readlane_b32 s48, v251, 40
	v_readlane_b32 s49, v251, 41
	v_readlane_b32 s50, v251, 42
	v_readlane_b32 s51, v251, 43
	s_add_i32 s0, s0, 0
	v_writelane_b32 v251, s88, 52
	v_writelane_b32 v254, s56, 35
	v_bfe_u32 v195, v0, 3, 2
	v_cmp_gt_u32_e64 s[2:3], 4, v194
	v_cmp_gt_u32_e64 s[4:5], 4, v196
	s_movk_i32 s83, 0x100
	v_or_b32_e32 v112, 1, v108
	v_or_b32_e32 v114, 2, v108
	v_or_b32_e32 v116, 3, v108
	v_or_b32_e32 v118, 0x100, v108
	v_or_b32_e32 v120, 0x101, v108
	v_or_b32_e32 v122, 0x102, v108
	v_or_b32_e32 v124, 0x103, v108
	v_or_b32_e32 v126, 0x200, v108
	v_or_b32_e32 v128, 0x201, v108
	v_or_b32_e32 v130, 0x202, v108
	v_or_b32_e32 v132, 0x203, v108
	v_or_b32_e32 v134, 0x300, v108
	v_or_b32_e32 v136, 0x301, v108
	v_or_b32_e32 v138, 0x302, v108
	v_or_b32_e32 v140, 0x303, v108
	v_or_b32_e32 v142, 0x400, v108
	v_or_b32_e32 v144, 0x401, v108
	v_or_b32_e32 v146, 0x402, v108
	v_or_b32_e32 v148, 0x403, v108
	v_or_b32_e32 v150, 0x500, v108
	v_or_b32_e32 v152, 0x501, v108
	v_or_b32_e32 v154, 0x502, v108
	v_or_b32_e32 v156, 0x503, v108
	v_or_b32_e32 v158, 0x600, v108
	v_or_b32_e32 v160, 0x601, v108
	v_or_b32_e32 v162, 0x602, v108
	v_or_b32_e32 v164, 0x603, v108
	v_or_b32_e32 v166, 0x700, v108
	v_or_b32_e32 v168, 0x701, v108
	v_or_b32_e32 v170, 0x702, v108
	v_or_b32_e32 v172, 0x703, v108
	v_or_b32_e32 v176, 0x801, v108
	v_writelane_b32 v253, s11, 42
	s_add_i32 s81, s0, 0xc800
	s_add_i32 s80, 0, 0x25040
	s_lshl_b32 s58, s8, 2
	s_movk_i32 s59, 0x2400
	v_lshlrev_b32_e32 v184, 2, v4
	s_movk_i32 s60, 0xff
	v_mov_b32_e32 v200, 1
	v_add_u32_e32 v201, v199, v151
	v_writelane_b32 v251, s89, 53
	v_writelane_b32 v254, s57, 36
	s_branch .LBB0_1072

.LBB0_1072:
	s_waitcnt vmcnt(0)
	s_barrier
	v_readfirstlane_b32 s0, v249
	s_cmp_lt_i32 s0, 0
	s_cbranch_scc1 .Lq_pop_s
	v_add_u32_e32 v2, 0xffffff00, v249
	v_mov_b32_e32 v249, -1
	s_branch .Lq_have_s
.Lq_pop_s:
	s_and_saveexec_b64 s[0:1], s[34:35]
	s_cbranch_execz .LBB0_1076
	s_mov_b64 s[8:9], exec
	v_mbcnt_lo_u32_b32 v1, s8, 0
	v_mbcnt_hi_u32_b32 v1, s9, v1
	v_cmp_eq_u32_e32 vcc, 0, v1
	s_and_saveexec_b64 s[6:7], vcc
	s_cbranch_execz .LBB0_1075
	s_bcnt1_i32_b64 s8, s[8:9]
	v_mov_b32_e32 v2, s8
	v_readlane_b32 s8, v253, 45
	v_readlane_b32 s9, v253, 46
	s_nop 4
	global_atomic_add v2, v99, v2, s[8:9] sc0

.LBB0_1076:
	s_or_b64 exec, exec, s[0:1]
	v_mov_b32_e32 v1, s80
	s_waitcnt lgkmcnt(0)
	s_barrier
	ds_read_b32 v2, v1
	s_waitcnt lgkmcnt(0)
	v_add_u32_e32 v2, 0xfffffe80, v2
.Lq_have_s:
	s_movk_i32 s0, 0x7f
	v_cmp_lt_i32_e32 vcc, s0, v2
	s_mov_b64 s[0:1], -1
	s_cbranch_vccnz .LBB0_1071
	v_lshlrev_b32_e32 v1, 2, v2
	v_add_u32_e32 v36, 0x2000, v1
	v_or_b32_e32 v4, v36, v195
	v_ashrrev_i32_e32 v5, 31, v4
	v_lshlrev_b64 v[6:7], 10, v[4:5]
	v_lshl_add_u64 v[6:7], v[100:101], 0, v[6:7]
	global_load_dwordx4 v[18:21], v[6:7], off
	global_load_dwordx4 v[22:25], v[6:7], off offset:32
	global_load_dwordx4 v[26:29], v[6:7], off offset:64
	global_load_dwordx4 v[30:33], v[6:7], off offset:96
	v_lshlrev_b64 v[4:5], 5, v[4:5]
	v_lshl_add_u64 v[4:5], v[102:103], 0, v[4:5]
	global_load_dword v37, v[4:5], off
	v_readlane_b32 s0, v252, 4
	v_lshlrev_b32_e32 v34, 4, v2
	v_readlane_b32 s1, v252, 5
	s_andn2_b64 vcc, exec, s[0:1]
	v_ashrrev_i32_e32 v35, 31, v34
	s_cbranch_vccnz .LBB0_1079
	v_readlane_b32 s8, v251, 28
	v_lshlrev_b64 v[2:3], 2, v[34:35]
	v_readlane_b32 s9, v251, 29
	v_mov_b32_e32 v4, s58
	v_readlane_b32 s10, v251, 30
	v_lshl_add_u64 v[2:3], s[8:9], 0, v[2:3]
	v_readlane_b32 s11, v251, 31
	v_readfirstlane_b32 s0, v2
	v_readfirstlane_b32 s1, v3
	v_readlane_b32 s12, v251, 32
	v_readlane_b32 s13, v251, 33
	v_readlane_b32 s14, v251, 34
	v_readlane_b32 s15, v251, 35
	v_readlane_b32 s16, v251, 36
	global_load_dword v2, v4, s[0:1]
	v_readlane_b32 s17, v251, 37
	v_readlane_b32 s18, v251, 38
	v_readlane_b32 s19, v251, 39
	v_readlane_b32 s20, v251, 40
	v_readlane_b32 s21, v251, 41
	v_readlane_b32 s22, v251, 42
	v_readlane_b32 s23, v251, 43
	s_waitcnt vmcnt(0)
	v_ashrrev_i32_e32 v3, 31, v2
	v_lshlrev_b64 v[2:3], 15, v[2:3]
	v_lshl_add_u64 v[38:39], v[104:105], 0, v[2:3]
	global_load_dwordx4 v[14:17], v[38:39], off offset:16
	global_load_dwordx4 v[78:81], v[38:39], off
	global_load_dwordx4 v[10:13], v[38:39], off offset:80
	global_load_dwordx4 v[74:77], v[38:39], off offset:64
	global_load_dwordx4 v[6:9], v[38:39], off offset:144
	global_load_dwordx4 v[70:73], v[38:39], off offset:128
	global_load_dwordx4 v[2:5], v[38:39], off offset:208
	global_load_dwordx4 v[66:69], v[38:39], off offset:192
